# P1: combined-modulation-vector loop rewritten (24 loads up front, one wait, 12 stores) instead of 12 dependent load-store round trips on workgroups 0-2
# baseline (speedup 1.0000x reference)
.LBB0_213:
	s_mov_b64 s[18:19], 0x1000
	s_mov_b64 s[20:21], 0x2000
	v_lshl_add_u64 v[224:225], v[14:15], 0, s[18:19]
	v_lshl_add_u64 v[226:227], v[0:1], 0, s[18:19]
	v_lshl_add_u64 v[230:231], v[4:5], 0, s[18:19]
	v_lshl_add_u64 v[234:235], v[6:7], 0, s[18:19]
	s_mov_b64 s[18:19], 0x109000
	v_lshl_add_u64 v[228:229], v[12:13], 0, s[18:19]
	v_lshl_add_u64 v[232:233], v[228:229], 0, s[20:21]
	s_mov_b64 s[18:19], 0x181000
	v_lshl_add_u64 v[236:237], v[10:11], 0, s[18:19]
	v_lshl_add_u64 v[238:239], v[236:237], 0, s[20:21]
	v_lshl_add_u64 v[240:241], v[238:239], 0, s[20:21]
	global_load_dword v200, v[224:225], off offset:-4096
	global_load_dword v201, v[226:227], off offset:-4096
	global_load_dword v202, v[228:229], off offset:-4096
	global_load_dword v203, v[230:231], off offset:-4096
	global_load_dword v204, v[232:233], off offset:-4096
	global_load_dword v205, v[234:235], off offset:-4096
	global_load_dword v206, v[224:225], off offset:-2048
	global_load_dword v207, v[226:227], off offset:-2048
	global_load_dword v208, v[228:229], off offset:-2048
	global_load_dword v209, v[230:231], off offset:-2048
	global_load_dword v210, v[232:233], off offset:-2048
	global_load_dword v211, v[234:235], off offset:-2048
	global_load_dword v212, v[224:225], off
	global_load_dword v213, v[226:227], off
	global_load_dword v214, v[228:229], off
	global_load_dword v215, v[230:231], off
	global_load_dword v216, v[232:233], off
	global_load_dword v217, v[234:235], off
	global_load_dword v218, v[224:225], off offset:2048
	global_load_dword v219, v[226:227], off offset:2048
	global_load_dword v220, v[228:229], off offset:2048
	global_load_dword v221, v[230:231], off offset:2048
	global_load_dword v222, v[232:233], off offset:2048
	global_load_dword v223, v[234:235], off offset:2048
	s_waitcnt vmcnt(0)
	v_mul_f32_e32 v200, v200, v201
	v_add_f32_e32 v202, 1.0, v202
	v_mul_f32_e32 v202, v203, v202
	v_mul_f32_e32 v204, v204, v205
	v_mul_f32_e32 v206, v206, v207
	v_add_f32_e32 v208, 1.0, v208
	v_mul_f32_e32 v208, v209, v208
	v_mul_f32_e32 v210, v210, v211
	v_mul_f32_e32 v212, v212, v213
	v_add_f32_e32 v214, 1.0, v214
	v_mul_f32_e32 v214, v215, v214
	v_mul_f32_e32 v216, v216, v217
	v_mul_f32_e32 v218, v218, v219
	v_add_f32_e32 v220, 1.0, v220
	v_mul_f32_e32 v220, v221, v220
	v_mul_f32_e32 v222, v222, v223
	global_store_dword v[236:237], v200, off offset:-4096
	global_store_dword v[238:239], v202, off offset:-4096
	global_store_dword v[240:241], v204, off offset:-4096
	global_store_dword v[236:237], v206, off offset:-2048
	global_store_dword v[238:239], v208, off offset:-2048
	global_store_dword v[240:241], v210, off offset:-2048
	global_store_dword v[236:237], v212, off
	global_store_dword v[238:239], v214, off
	global_store_dword v[240:241], v216, off
	global_store_dword v[236:237], v218, off offset:2048
	global_store_dword v[238:239], v220, off offset:2048
	global_store_dword v[240:241], v222, off offset:2048
	s_branch .LBB0_210
